# top-16 block search: the three forced blocks go straight into slots 0-2 (13 search rounds instead of 16)
# baseline (speedup 1.0000x reference)
; #define LAS __attribute__((address_space(3)))
; __device__ __forceinline__ void nsa_wave(CArgs* Ap, int l, int b, int g, int tq0, const LAS float* lut, LAS float* imp, int lane) {
;     ...
;         const int sq = lane >> 4, tsel = tq0 + sq; (void)tsel;
;         float sc[8];
; #pragma unroll
;         for (int jj = 0; jj < 8; ++jj) { const int j = n16 + 16 * jj;
;             float v;
;             if (j > cur) v = -1.f;
;             else if (j == 0 || j == cur || j == cur - 1) v = 1e4f;
;             else { const LAS float* ip = imp + sq * 512 + 4 * j; v = ip[0] + 2.f * (ip[-1] + ip[-2] + ip[-3]) + ip[-4]; }
;             sc[jj] = v; }
;         for (int s = 0; s < 16; ++s) {
;             float bv = sc[0]; int bj = n16;
; #pragma unroll
;             for (int jj = 1; jj < 8; ++jj) if (sc[jj] > bv) { bv = sc[jj]; bj = n16 + 16 * jj; }
; #pragma unroll
;             for (int off = 1; off < 16; off <<= 1) { const float ov = __shfl_xor(bv, off); const int oj = __shfl_xor(bj, off); if (ov > bv || (ov == bv && oj < bj)) { bv = ov; bj = oj; } }
;             if (n16 == s) selreg = (bv >= 0.f) ? bj : -1;
; #pragma unroll
;             for (int jj = 0; jj < 8; ++jj) if (bj == n16 + 16 * jj) sc[jj] = -2.f;
.Ltk_full:
	s_add_i32 s22, s21, -1
	v_lshrrev_b32_e32 v106, 4, v89
	v_lshl_add_u32 v106, v106, 11, s93
	v_lshl_add_u32 v106, v128, 4, v106
	v_add_u32_e32 v107, -16, v106
	v_or_b32_e32 v99, 16, v128
	v_or_b32_e32 v100, 32, v128
	v_or_b32_e32 v101, 48, v128
	v_or_b32_e32 v102, 64, v128
	v_or_b32_e32 v103, 80, v128
	v_or_b32_e32 v104, 96, v128
	v_or_b32_e32 v105, 112, v128
	ds_read_b128 v[24:27], v107
	ds_read_b32 v56, v106
	ds_read_b128 v[28:31], v107 offset:256
	ds_read_b32 v57, v106 offset:256
	ds_read_b128 v[32:35], v107 offset:512
	ds_read_b32 v58, v106 offset:512
	ds_read_b128 v[36:39], v107 offset:768
	ds_read_b32 v59, v106 offset:768
	ds_read_b128 v[40:43], v107 offset:1024
	ds_read_b32 v60, v106 offset:1024
	ds_read_b128 v[44:47], v107 offset:1280
	ds_read_b32 v61, v106 offset:1280
	ds_read_b128 v[48:51], v107 offset:1536
	ds_read_b32 v62, v106 offset:1536
	ds_read_b128 v[52:55], v107 offset:1792
	ds_read_b32 v63, v106 offset:1792
	v_mov_b32_e32 v64, 0x461c4000
	v_cmp_eq_u32_e64 s[46:47], s21, v128
	v_cmp_eq_u32_e64 s[48:49], s22, v128
	s_or_b64 s[50:51], s[46:47], s[48:49]
	s_or_b64 s[50:51], s[50:51], s[4:5]
	v_cmp_eq_u32_e64 s[46:47], s21, v99
	v_cmp_eq_u32_e64 s[48:49], s22, v99
	s_or_b64 s[52:53], s[46:47], s[48:49]
	v_cmp_eq_u32_e64 s[46:47], s21, v100
	v_cmp_eq_u32_e64 s[48:49], s22, v100
	s_or_b64 s[54:55], s[46:47], s[48:49]
	v_cmp_eq_u32_e64 s[46:47], s21, v101
	v_cmp_eq_u32_e64 s[48:49], s22, v101
	s_or_b64 s[56:57], s[46:47], s[48:49]
	v_cmp_eq_u32_e64 s[46:47], s21, v102
	v_cmp_eq_u32_e64 s[48:49], s22, v102
	s_or_b64 s[58:59], s[46:47], s[48:49]
	v_cmp_eq_u32_e64 s[46:47], s21, v103
	v_cmp_eq_u32_e64 s[48:49], s22, v103
	s_or_b64 s[60:61], s[46:47], s[48:49]
	v_cmp_eq_u32_e64 s[46:47], s21, v104
	v_cmp_eq_u32_e64 s[48:49], s22, v104
	s_or_b64 s[62:63], s[46:47], s[48:49]
	v_cmp_eq_u32_e64 s[46:47], s21, v105
	v_cmp_eq_u32_e64 s[48:49], s22, v105
	s_or_b64 s[64:65], s[46:47], s[48:49]
	s_waitcnt lgkmcnt(14)
	v_add_f32_e32 v26, v27, v26
	v_add_f32_e32 v25, v26, v25
	v_fmac_f32_e32 v56, 2.0, v25
	v_add_f32_e32 v228, v24, v56
	s_waitcnt lgkmcnt(12)
	v_add_f32_e32 v30, v31, v30
	v_add_f32_e32 v29, v30, v29
	v_fmac_f32_e32 v57, 2.0, v29
	v_add_f32_e32 v229, v28, v57
	s_waitcnt lgkmcnt(10)
	v_add_f32_e32 v34, v35, v34
	v_add_f32_e32 v33, v34, v33
	v_fmac_f32_e32 v58, 2.0, v33
	v_add_f32_e32 v230, v32, v58
	s_waitcnt lgkmcnt(8)
	v_add_f32_e32 v38, v39, v38
	v_add_f32_e32 v37, v38, v37
	v_fmac_f32_e32 v59, 2.0, v37
	v_add_f32_e32 v231, v36, v59
	s_waitcnt lgkmcnt(6)
	v_add_f32_e32 v42, v43, v42
	v_add_f32_e32 v41, v42, v41
	v_fmac_f32_e32 v60, 2.0, v41
	v_add_f32_e32 v232, v40, v60
	s_waitcnt lgkmcnt(4)
	v_add_f32_e32 v46, v47, v46
	v_add_f32_e32 v45, v46, v45
	v_fmac_f32_e32 v61, 2.0, v45
	v_add_f32_e32 v233, v44, v61
	s_waitcnt lgkmcnt(2)
	v_add_f32_e32 v50, v51, v50
	v_add_f32_e32 v49, v50, v49
	v_fmac_f32_e32 v62, 2.0, v49
	v_add_f32_e32 v234, v48, v62
	s_waitcnt lgkmcnt(0)
	v_add_f32_e32 v54, v55, v54
	v_add_f32_e32 v53, v54, v53
	v_fmac_f32_e32 v63, 2.0, v53
	v_add_f32_e32 v235, v52, v63
	v_mov_b32_e32 v239, -2.0
	v_cndmask_b32_e64 v228, v228, v239, s[50:51]
	v_cndmask_b32_e64 v229, v229, v239, s[52:53]
	v_cndmask_b32_e64 v230, v230, v239, s[54:55]
	v_cndmask_b32_e64 v231, v231, v239, s[56:57]
	v_cndmask_b32_e64 v232, v232, v239, s[58:59]
	v_cndmask_b32_e64 v233, v233, v239, s[60:61]
	v_cndmask_b32_e64 v234, v234, v239, s[62:63]
	v_cndmask_b32_e64 v235, v235, v239, s[64:65]
	v_cmp_eq_u32_e64 s[46:47], 1, v128
	v_cmp_eq_u32_e64 s[48:49], 2, v128
	v_mov_b32_e32 v238, s22
	v_mov_b32_e32 v239, s21
	v_cmp_eq_u32_e32 vcc, 0, v128
	v_cndmask_b32_e64 v210, v210, v238, s[46:47]
	v_cndmask_b32_e64 v210, v210, v239, s[48:49]
	v_cndmask_b32_e64 v210, v210, 0, vcc
	v_cmp_ge_i32_e64 s[52:53], s21, v99
	v_cmp_ge_i32_e64 s[54:55], s21, v100
	v_cmp_ge_i32_e64 s[56:57], s21, v101
	v_cmp_ge_i32_e64 s[58:59], s21, v102
	v_cmp_ge_i32_e64 s[60:61], s21, v103
	v_cmp_ge_i32_e64 s[62:63], s21, v104
	v_cmp_ge_i32_e64 s[64:65], s21, v105
	v_cndmask_b32_e64 v229, -1.0, v229, s[52:53]
	v_cndmask_b32_e64 v230, -1.0, v230, s[54:55]
	v_cndmask_b32_e64 v231, -1.0, v231, s[56:57]
	v_cndmask_b32_e64 v232, -1.0, v232, s[58:59]
	v_cndmask_b32_e64 v233, -1.0, v233, s[60:61]
	v_cndmask_b32_e64 v234, -1.0, v234, s[62:63]
	v_cndmask_b32_e64 v235, -1.0, v235, s[64:65]
	s_mov_b32 s23, 3
